# GEMM main-loop labels aligned to 64 bytes (code placement)
# baseline (speedup 1.0000x reference)
; #define PG8_STAGE(bufoff, gbase, voff) do { _Pragma("unroll") for (int _i = 0; _i < 2; ++_i) \
;         __builtin_amdgcn_global_load_lds((const unsigned*)((const char*)(gbase) + (voff)[_i]), (LAS unsigned*)(lds + (bufoff) + ldsw + _i * 8192), 16, 0, 0); } while (0)
; #define PG8_WAIT_V(n) asm volatile("s_waitcnt vmcnt(" #n ")" ::: "memory")
; #define PG8_BAR __builtin_amdgcn_s_barrier()
; template <class Epi>
; __device__ __forceinline__ void gemm_phase(LAS unsigned char* lds, const Gemm g, const StaticOrder& S, const Epi& E, const int tid) {
;     ...
;                 for (int n = 0; n < 2; ++n) acc[a][b][m][n] = (f32x4){0.f, 0.f, 0.f, 0.f};
;     bf16x8 At[4][2], B0[2][2], B1[2][2];
;     const char* cA = (const char*)g.A + (size_t)cur.pm * tstepA + (size_t)cur.pn * pnoffA; const char* cB = (const char*)g.Bt + (size_t)cur.pn * tstepB;
;     PG8_STAGE(PG8_SB(0, 0), cB, voffB); PG8_STAGE(PG8_SB(0, 1), cB + hstepB, voffB); PG8_STAGE(PG8_SA(0, 0), cA, voffA); PG8_STAGE(PG8_SA(0, 1), cA + hstepA, voffA);
;     if (wr == 1) PG8_BAR;
;     PG8_WAIT_V(2); PG8_BAR;
;     PG8_STAGE(PG8_SB(1, 0), cB + kstep, voffB); PG8_STAGE(PG8_SA(1, 0), cA + kstepA, voffA); PG8_STAGE(PG8_SB(1, 1), cB + hstepB + kstep, voffB);
;     PG8_WAIT_V(6); PG8_BAR;
;     for (;;) {
;         const bool has_next = S.next(ui + 1, nxt);
;         const char* nA = has_next ? (const char*)g.A + (size_t)nxt.pm * tstepA + (size_t)nxt.pn * pnoffA : cA; const char* nB = has_next ? (const char*)g.Bt + (size_t)nxt.pn * tstepB : cB;
;         for (int t = 0; t < nt; t += 2) {
;             const bool last = (t == nt - 2);
;             const char* a1 = cA + (size_t)(t + 1) * kstepA;
;             const char* a2 = last ? nA : cA + (size_t)(t + 2) * kstepA; const char* b2 = last ? nB : cB + (size_t)(t + 2) * kstep;
;             const char* a3 = a2 + kstepA; const char* b3 = b2 + kstep;
;             PG8_LDB(B0, 0, 0); PG8_LDB(B1, 0, 1); PG8_SCHED; PG8_LDA(At, 0, 0); PG8_STAGE(PG8_SA(1, 1), a1 + hstepA, voffA);
;             PG8_WAIT_V(8); PG8_WAIT_L(0); PG8_BAR; PG8_MMA(0, 0, At, B0); PG8_MMA(0, 1, At, B1); PG8_BAR; PG8_SCHED;
;             PG8_LDA(At, 0, 1); PG8_STAGE(PG8_SB(0, 0), b2, voffB); PG8_STAGE(PG8_SB(0, 1), b2 + hstepB, voffB); PG8_STAGE(PG8_SA(0, 0), a2, voffA);
;             PG8_WAIT_V(8); PG8_WAIT_L(0); PG8_BAR; PG8_MMA(1, 0, At, B0); PG8_MMA(1, 1, At, B1); PG8_BAR; PG8_SCHED;
.LBB0_224:
	s_ashr_i32 s11, s10, 31
	s_lshl_b64 s[12:13], s[10:11], 19
	s_add_u32 s12, s24, s12
	s_addc_u32 s13, s25, s13
	s_and_b64 s[14:15], s[4:5], exec
	s_cselect_b32 s11, s13, s17
	s_cselect_b32 s47, s12, s16
	s_ashr_i32 s9, s8, 31
	s_lshl_b64 s[14:15], s[8:9], 19
	s_add_u32 s14, s84, s14
	s_addc_u32 s15, s85, s15
	s_and_b64 s[34:35], s[4:5], exec
	s_cselect_b32 s9, s15, s29
	s_cselect_b32 s48, s14, s28
	s_add_u32 s49, s28, 0x100
	s_addc_u32 s50, s29, 0
	s_mov_b32 s51, -2
	s_add_u32 s28, s16, 0x1000
	s_addc_u32 s29, s17, 0
	s_add_i32 s52, 0, 0x10000
	s_cmp_eq_u32 s51, 12
	s_cselect_b32 s41, s11, s29
	s_cselect_b32 s40, s47, s28
	s_cselect_b32 s35, s9, s50
	s_cselect_b32 s34, s48, s49
	s_add_i32 s53, 0, 0x14000
	v_add_u32_e32 v140, s52, v175
	v_add_u32_e32 v164, s53, v175
	ds_read_b128 v[128:131], v140
	ds_read_b128 v[132:135], v140 offset:1024
	ds_read_b128 v[136:139], v140 offset:2048
	ds_read_b128 v[140:143], v140 offset:3072
	ds_read_b128 v[156:159], v164
	ds_read_b128 v[160:163], v164 offset:1024
	ds_read_b128 v[168:171], v164 offset:2048
	ds_read_b128 v[178:181], v164 offset:3072
	v_lshl_add_u64 v[164:165], s[16:17], 0, v[152:153]
	s_add_i32 m0, s21, 0xc000
	ds_read_b128 v[202:205], v196
	ds_read_b128 v[206:209], v196 offset:1024
	ds_read_b128 v[210:213], v196 offset:2048
	ds_read_b128 v[214:217], v196 offset:3072
	ds_read_b128 v[226:229], v196 offset:4096
	ds_read_b128 v[230:233], v196 offset:5120
	ds_read_b128 v[234:237], v196 offset:6144
	ds_read_b128 v[238:241], v196 offset:7168
	global_load_lds_dwordx4 v[164:165], off
	v_lshl_add_u64 v[164:165], s[16:17], 0, v[154:155]
	s_add_i32 m0, s21, 0xe000
	s_nop 0
	global_load_lds_dwordx4 v[164:165], off
	s_waitcnt vmcnt(8)
	s_waitcnt lgkmcnt(0)
	s_barrier
	v_mfma_f32_16x16x32_bf16 v[124:127], v[128:131], v[202:205], 0
	v_mfma_f32_16x16x32_bf16 v[120:123], v[136:139], v[202:205], 0
	v_mfma_f32_16x16x32_bf16 v[116:119], v[128:131], v[210:213], 0
	v_mfma_f32_16x16x32_bf16 v[108:111], v[136:139], v[210:213], 0
	v_mfma_f32_16x16x32_bf16 v[100:103], v[128:131], v[226:229], 0
	v_mfma_f32_16x16x32_bf16 v[92:95], v[136:139], v[226:229], 0
	v_mfma_f32_16x16x32_bf16 v[84:87], v[128:131], v[234:237], 0
	v_mfma_f32_16x16x32_bf16 v[76:79], v[136:139], v[234:237], 0
	v_mfma_f32_16x16x32_bf16 v[124:127], v[132:135], v[206:209], v[124:127]
	v_mfma_f32_16x16x32_bf16 v[120:123], v[140:143], v[206:209], v[120:123]
	v_mfma_f32_16x16x32_bf16 v[116:119], v[132:135], v[214:217], v[116:119]
	v_mfma_f32_16x16x32_bf16 v[108:111], v[140:143], v[214:217], v[108:111]
	v_mfma_f32_16x16x32_bf16 v[100:103], v[132:135], v[230:233], v[100:103]
	v_mfma_f32_16x16x32_bf16 v[92:95], v[140:143], v[230:233], v[92:95]
	v_mfma_f32_16x16x32_bf16 v[84:87], v[132:135], v[238:241], v[84:87]
	v_mfma_f32_16x16x32_bf16 v[76:79], v[140:143], v[238:241], v[76:79]
	v_mfma_f32_16x16x32_bf16 v[112:115], v[156:159], v[202:205], 0
	v_mfma_f32_16x16x32_bf16 v[104:107], v[168:171], v[202:205], 0
	v_mfma_f32_16x16x32_bf16 v[96:99], v[156:159], v[210:213], 0
	v_mfma_f32_16x16x32_bf16 v[88:91], v[168:171], v[210:213], 0
	v_mfma_f32_16x16x32_bf16 v[80:83], v[156:159], v[226:229], 0
	v_mfma_f32_16x16x32_bf16 v[72:75], v[168:171], v[226:229], 0
	v_mfma_f32_16x16x32_bf16 v[68:71], v[156:159], v[234:237], 0
	v_mfma_f32_16x16x32_bf16 v[64:67], v[168:171], v[234:237], 0
	v_mfma_f32_16x16x32_bf16 v[112:115], v[160:163], v[206:209], v[112:115]
	v_mfma_f32_16x16x32_bf16 v[104:107], v[178:181], v[206:209], v[104:107]
	v_mfma_f32_16x16x32_bf16 v[96:99], v[160:163], v[214:217], v[96:99]
	v_mfma_f32_16x16x32_bf16 v[88:91], v[178:181], v[214:217], v[88:91]
	v_mfma_f32_16x16x32_bf16 v[80:83], v[160:163], v[230:233], v[80:83]
	v_mfma_f32_16x16x32_bf16 v[72:75], v[178:181], v[230:233], v[72:75]
	v_mfma_f32_16x16x32_bf16 v[68:71], v[160:163], v[238:241], v[68:71]
	v_mfma_f32_16x16x32_bf16 v[64:67], v[178:181], v[238:241], v[64:67]
	s_barrier
	s_add_i32 s16, s52, s20
	v_lshl_add_u64 v[164:165], s[34:35], 0, v[176:177]
	s_mov_b32 m0, s16
	ds_read_b128 v[202:205], v196 offset:16384
	ds_read_b128 v[206:209], v196 offset:17408
	ds_read_b128 v[210:213], v196 offset:18432
	ds_read_b128 v[214:217], v196 offset:19456
	ds_read_b128 v[226:229], v196 offset:20480
	ds_read_b128 v[230:233], v196 offset:21504
	ds_read_b128 v[234:237], v196 offset:22528
	ds_read_b128 v[238:241], v196 offset:23552
	global_load_lds_dwordx4 v[164:165], off
	s_add_i32 m0, s16, 0x2000
	s_add_u32 s16, s34, 0x40000
	v_lshl_add_u64 v[172:173], s[34:35], 0, v[144:145]
	s_addc_u32 s17, s35, 0
	s_add_i32 s52, s53, s20
	global_load_lds_dwordx4 v[172:173], off
	v_lshl_add_u64 v[194:195], s[16:17], 0, v[176:177]
	s_mov_b32 m0, s52
	v_lshl_add_u64 v[198:199], s[40:41], 0, v[146:147]
	global_load_lds_dwordx4 v[194:195], off
	v_lshl_add_u64 v[194:195], s[16:17], 0, v[144:145]
	s_add_i32 m0, s52, 0x2000
	s_nop 0
	global_load_lds_dwordx4 v[194:195], off
	v_lshl_add_u64 v[194:195], s[40:41], 0, v[148:149]
	s_mov_b32 m0, s21
	s_nop 0
	global_load_lds_dwordx4 v[194:195], off
	s_mov_b32 m0, s22
	s_nop 0
	global_load_lds_dwordx4 v[198:199], off
	s_waitcnt vmcnt(8)
	s_waitcnt lgkmcnt(0)
	s_barrier
; #define PG8_STAGE(bufoff, gbase, voff) do { _Pragma("unroll") for (int _i = 0; _i < 2; ++_i) \
;         __builtin_amdgcn_global_load_lds((const unsigned*)((const char*)(gbase) + (voff)[_i]), (LAS unsigned*)(lds + (bufoff) + ldsw + _i * 8192), 16, 0, 0); } while (0)
; #define PG8_LDA(dst, b, h) do { _Pragma("unroll") for (int m = 0; m < 4; ++m) _Pragma("unroll") for (int k = 0; k < 2; ++k) dst[m][k] = *(const LAS bf16x8*)(lds + PG8_SA(b, h) + aoff + m * 2048 + k * 1024); } while (0)
; #define PG8_LDB(dst, b, h) do { _Pragma("unroll") for (int n = 0; n < 2; ++n) _Pragma("unroll") for (int k = 0; k < 2; ++k) dst[n][k] = *(const LAS bf16x8*)(lds + PG8_SB(b, h) + boff + n * 2048 + k * 1024); } while (0)
; #define PG8_MMA(ai, bj, At, Bt) do { __builtin_amdgcn_s_setprio(1); _Pragma("unroll") for (int m = 0; m < 4; ++m) _Pragma("unroll") for (int n = 0; n < 2; ++n) _Pragma("unroll") for (int k = 0; k < 2; ++k) \
;         acc[ai][bj][m][n] = __builtin_amdgcn_mfma_f32_16x16x32_bf16(Bt[n][k], At[m][k], acc[ai][bj][m][n], 0, 0, 0); __builtin_amdgcn_s_setprio(0); } while (0)
; #define PG8_WAIT_V(n) asm volatile("s_waitcnt vmcnt(" #n ")" ::: "memory")
; #define PG8_WAIT_L(n) asm volatile("s_waitcnt lgkmcnt(" #n ")" ::: "memory")
; #define PG8_BAR __builtin_amdgcn_s_barrier()
; #define PG8_SCHED __builtin_amdgcn_sched_barrier(0)
; template <class Epi>
; __device__ __forceinline__ void gemm_phase(LAS unsigned char* lds, const Gemm g, const StaticOrder& S, const Epi& E, const int tid) {
;     ...
;             PG8_WAIT_V(8); PG8_WAIT_L(0); PG8_BAR; PG8_MMA(1, 0, At, B0); PG8_MMA(1, 1, At, B1); PG8_BAR; PG8_SCHED;
;             PG8_LDB(B0, 1, 0); PG8_LDB(B1, 1, 1); PG8_SCHED; PG8_LDA(At, 1, 0); PG8_STAGE(PG8_SA(0, 1), a2 + hstepA, voffA);
;             PG8_WAIT_V(8); PG8_WAIT_L(0); PG8_BAR; PG8_MMA(0, 0, At, B0); PG8_MMA(0, 1, At, B1); PG8_BAR; PG8_SCHED;
;             PG8_LDA(At, 1, 1); PG8_STAGE(PG8_SB(1, 0), b3, voffB); PG8_STAGE(PG8_SB(1, 1), b3 + hstepB, voffB); PG8_STAGE(PG8_SA(1, 0), a3, voffA);
	v_mfma_f32_16x16x32_bf16 v[60:63], v[128:131], v[202:205], 0
	v_mfma_f32_16x16x32_bf16 v[56:59], v[136:139], v[202:205], 0
	v_mfma_f32_16x16x32_bf16 v[52:55], v[128:131], v[210:213], 0
	v_mfma_f32_16x16x32_bf16 v[44:47], v[136:139], v[210:213], 0
	v_mfma_f32_16x16x32_bf16 v[36:39], v[128:131], v[226:229], 0
	v_mfma_f32_16x16x32_bf16 v[28:31], v[136:139], v[226:229], 0
	v_mfma_f32_16x16x32_bf16 v[20:23], v[128:131], v[234:237], 0
	v_mfma_f32_16x16x32_bf16 v[12:15], v[136:139], v[234:237], 0
	v_mfma_f32_16x16x32_bf16 v[60:63], v[132:135], v[206:209], v[60:63]
	v_mfma_f32_16x16x32_bf16 v[56:59], v[140:143], v[206:209], v[56:59]
	v_mfma_f32_16x16x32_bf16 v[52:55], v[132:135], v[214:217], v[52:55]
	v_mfma_f32_16x16x32_bf16 v[44:47], v[140:143], v[214:217], v[44:47]
	v_mfma_f32_16x16x32_bf16 v[36:39], v[132:135], v[230:233], v[36:39]
	v_mfma_f32_16x16x32_bf16 v[28:31], v[140:143], v[230:233], v[28:31]
	v_mfma_f32_16x16x32_bf16 v[20:23], v[132:135], v[238:241], v[20:23]
	v_mfma_f32_16x16x32_bf16 v[12:15], v[140:143], v[238:241], v[12:15]
	v_mfma_f32_16x16x32_bf16 v[48:51], v[156:159], v[202:205], 0
	v_mfma_f32_16x16x32_bf16 v[40:43], v[168:171], v[202:205], 0
	v_mfma_f32_16x16x32_bf16 v[32:35], v[156:159], v[210:213], 0
	v_mfma_f32_16x16x32_bf16 v[24:27], v[168:171], v[210:213], 0
	v_mfma_f32_16x16x32_bf16 v[16:19], v[156:159], v[226:229], 0
	v_mfma_f32_16x16x32_bf16 v[8:11], v[168:171], v[226:229], 0
	v_mfma_f32_16x16x32_bf16 v[4:7], v[156:159], v[234:237], 0
	v_mfma_f32_16x16x32_bf16 v[0:3], v[168:171], v[234:237], 0
	v_mfma_f32_16x16x32_bf16 v[48:51], v[160:163], v[206:209], v[48:51]
	v_mfma_f32_16x16x32_bf16 v[40:43], v[178:181], v[206:209], v[40:43]
	v_mfma_f32_16x16x32_bf16 v[32:35], v[160:163], v[214:217], v[32:35]
	v_mfma_f32_16x16x32_bf16 v[24:27], v[178:181], v[214:217], v[24:27]
	v_mfma_f32_16x16x32_bf16 v[16:19], v[160:163], v[230:233], v[16:19]
	v_mfma_f32_16x16x32_bf16 v[8:11], v[178:181], v[230:233], v[8:11]
	v_mfma_f32_16x16x32_bf16 v[4:7], v[160:163], v[238:241], v[4:7]
	v_mfma_f32_16x16x32_bf16 v[0:3], v[178:181], v[238:241], v[0:3]
	s_barrier
	s_add_i32 s52, 0, 0x18000
	s_add_i32 s53, 0, 0x1c000
	v_add_u32_e32 v140, s52, v175
	v_add_u32_e32 v166, s53, v175
	ds_read_b128 v[128:131], v140
	ds_read_b128 v[132:135], v140 offset:1024
	ds_read_b128 v[136:139], v140 offset:2048
	ds_read_b128 v[140:143], v140 offset:3072
	ds_read_b128 v[156:159], v166
	ds_read_b128 v[160:163], v166 offset:1024
	ds_read_b128 v[168:171], v166 offset:2048
	ds_read_b128 v[178:181], v166 offset:3072
	s_add_u32 s16, s40, 0x40000
	s_addc_u32 s17, s41, 0
	s_mov_b32 m0, s23
	v_lshl_add_u64 v[218:219], s[16:17], 0, v[148:149]
	ds_read_b128 v[202:205], v196 offset:32768
	ds_read_b128 v[206:209], v196 offset:33792
	ds_read_b128 v[210:213], v196 offset:34816
	ds_read_b128 v[214:217], v196 offset:35840
	ds_read_b128 v[226:229], v196 offset:36864
	ds_read_b128 v[230:233], v196 offset:37888
	ds_read_b128 v[234:237], v196 offset:38912
	ds_read_b128 v[238:241], v196 offset:39936
	global_load_lds_dwordx4 v[218:219], off
	v_lshl_add_u64 v[218:219], s[16:17], 0, v[146:147]
	s_mov_b32 m0, s30
	s_nop 0
	global_load_lds_dwordx4 v[218:219], off
	s_waitcnt vmcnt(8)
	s_waitcnt lgkmcnt(0)
	s_barrier
	v_mfma_f32_16x16x32_bf16 v[124:127], v[128:131], v[202:205], v[124:127]
	v_mfma_f32_16x16x32_bf16 v[120:123], v[136:139], v[202:205], v[120:123]
	v_mfma_f32_16x16x32_bf16 v[116:119], v[128:131], v[210:213], v[116:119]
	v_mfma_f32_16x16x32_bf16 v[108:111], v[136:139], v[210:213], v[108:111]
	v_mfma_f32_16x16x32_bf16 v[100:103], v[128:131], v[226:229], v[100:103]
	v_mfma_f32_16x16x32_bf16 v[92:95], v[136:139], v[226:229], v[92:95]
	v_mfma_f32_16x16x32_bf16 v[84:87], v[128:131], v[234:237], v[84:87]
	v_mfma_f32_16x16x32_bf16 v[76:79], v[136:139], v[234:237], v[76:79]
	v_mfma_f32_16x16x32_bf16 v[124:127], v[132:135], v[206:209], v[124:127]
	v_mfma_f32_16x16x32_bf16 v[120:123], v[140:143], v[206:209], v[120:123]
	v_mfma_f32_16x16x32_bf16 v[116:119], v[132:135], v[214:217], v[116:119]
	v_mfma_f32_16x16x32_bf16 v[108:111], v[140:143], v[214:217], v[108:111]
	v_mfma_f32_16x16x32_bf16 v[100:103], v[132:135], v[230:233], v[100:103]
	v_mfma_f32_16x16x32_bf16 v[92:95], v[140:143], v[230:233], v[92:95]
	v_mfma_f32_16x16x32_bf16 v[84:87], v[132:135], v[238:241], v[84:87]
	v_mfma_f32_16x16x32_bf16 v[76:79], v[140:143], v[238:241], v[76:79]
	v_mfma_f32_16x16x32_bf16 v[112:115], v[156:159], v[202:205], v[112:115]
	v_mfma_f32_16x16x32_bf16 v[104:107], v[168:171], v[202:205], v[104:107]
	v_mfma_f32_16x16x32_bf16 v[96:99], v[156:159], v[210:213], v[96:99]
	v_mfma_f32_16x16x32_bf16 v[88:91], v[168:171], v[210:213], v[88:91]
	v_mfma_f32_16x16x32_bf16 v[80:83], v[156:159], v[226:229], v[80:83]
	v_mfma_f32_16x16x32_bf16 v[72:75], v[168:171], v[226:229], v[72:75]
	v_mfma_f32_16x16x32_bf16 v[68:71], v[156:159], v[234:237], v[68:71]
	v_mfma_f32_16x16x32_bf16 v[64:67], v[168:171], v[234:237], v[64:67]
	v_mfma_f32_16x16x32_bf16 v[112:115], v[160:163], v[206:209], v[112:115]
	v_mfma_f32_16x16x32_bf16 v[104:107], v[178:181], v[206:209], v[104:107]
	v_mfma_f32_16x16x32_bf16 v[96:99], v[160:163], v[214:217], v[96:99]
	v_mfma_f32_16x16x32_bf16 v[88:91], v[178:181], v[214:217], v[88:91]
	v_mfma_f32_16x16x32_bf16 v[80:83], v[160:163], v[230:233], v[80:83]
	v_mfma_f32_16x16x32_bf16 v[72:75], v[178:181], v[230:233], v[72:75]
	v_mfma_f32_16x16x32_bf16 v[68:71], v[160:163], v[238:241], v[68:71]
	v_mfma_f32_16x16x32_bf16 v[64:67], v[178:181], v[238:241], v[64:67]
	s_barrier
; #define PG8_STAGE(bufoff, gbase, voff) do { _Pragma("unroll") for (int _i = 0; _i < 2; ++_i) \
;         __builtin_amdgcn_global_load_lds((const unsigned*)((const char*)(gbase) + (voff)[_i]), (LAS unsigned*)(lds + (bufoff) + ldsw + _i * 8192), 16, 0, 0); } while (0)
; #define PG8_LDA(dst, b, h) do { _Pragma("unroll") for (int m = 0; m < 4; ++m) _Pragma("unroll") for (int k = 0; k < 2; ++k) dst[m][k] = *(const LAS bf16x8*)(lds + PG8_SA(b, h) + aoff + m * 2048 + k * 1024); } while (0)
; #define PG8_MMA(ai, bj, At, Bt) do { __builtin_amdgcn_s_setprio(1); _Pragma("unroll") for (int m = 0; m < 4; ++m) _Pragma("unroll") for (int n = 0; n < 2; ++n) _Pragma("unroll") for (int k = 0; k < 2; ++k) \
;         acc[ai][bj][m][n] = __builtin_amdgcn_mfma_f32_16x16x32_bf16(Bt[n][k], At[m][k], acc[ai][bj][m][n], 0, 0, 0); __builtin_amdgcn_s_setprio(0); } while (0)
; #define PG8_WAIT_V(n) asm volatile("s_waitcnt vmcnt(" #n ")" ::: "memory")
; #define PG8_WAIT_L(n) asm volatile("s_waitcnt lgkmcnt(" #n ")" ::: "memory")
; #define PG8_BAR __builtin_amdgcn_s_barrier()
; #define PG8_SCHED __builtin_amdgcn_sched_barrier(0)
; template <class Epi>
; __device__ __forceinline__ void gemm_phase(LAS unsigned char* lds, const Gemm g, const StaticOrder& S, const Epi& E, const int tid) {
;     ...
;             PG8_LDA(At, 1, 1); PG8_STAGE(PG8_SB(1, 0), b3, voffB); PG8_STAGE(PG8_SB(1, 1), b3 + hstepB, voffB); PG8_STAGE(PG8_SA(1, 0), a3, voffA);
;             PG8_WAIT_V(8); PG8_WAIT_L(0); PG8_BAR; PG8_MMA(1, 0, At, B0); PG8_MMA(1, 1, At, B1); PG8_BAR; PG8_SCHED;
;         }
	s_add_i32 s16, s52, s20
	v_lshl_add_u64 v[164:165], v[164:165], 0, s[36:37]
	s_mov_b32 m0, s16
	ds_read_b128 v[202:205], v196 offset:49152
	ds_read_b128 v[206:209], v196 offset:50176
	ds_read_b128 v[210:213], v196 offset:51200
	ds_read_b128 v[214:217], v196 offset:52224
	ds_read_b128 v[226:229], v196 offset:53248
	ds_read_b128 v[230:233], v196 offset:54272
	ds_read_b128 v[234:237], v196 offset:55296
	ds_read_b128 v[238:241], v196 offset:56320
	global_load_lds_dwordx4 v[164:165], off
	s_add_i32 m0, s16, 0x2000
	s_add_u32 s16, s34, 0x40080
	v_lshl_add_u64 v[164:165], v[172:173], 0, s[36:37]
	s_addc_u32 s17, s35, 0
	s_add_i32 s34, s53, s20
	global_load_lds_dwordx4 v[164:165], off
	v_lshl_add_u64 v[164:165], s[16:17], 0, v[176:177]
	s_mov_b32 m0, s34
	s_nop 0
	global_load_lds_dwordx4 v[164:165], off
	v_lshl_add_u64 v[164:165], s[16:17], 0, v[144:145]
	s_add_i32 m0, s34, 0x2000
	s_nop 0
	global_load_lds_dwordx4 v[164:165], off
	v_lshl_add_u64 v[164:165], v[194:195], 0, s[76:77]
	s_mov_b32 m0, s42
	s_nop 0
	global_load_lds_dwordx4 v[164:165], off
	v_lshl_add_u64 v[164:165], v[198:199], 0, s[76:77]
	s_mov_b32 m0, s43
	s_nop 0
	global_load_lds_dwordx4 v[164:165], off
	s_waitcnt vmcnt(8)
	s_waitcnt lgkmcnt(0)
	s_barrier
	v_mfma_f32_16x16x32_bf16 v[60:63], v[128:131], v[202:205], v[60:63]
	v_mfma_f32_16x16x32_bf16 v[56:59], v[136:139], v[202:205], v[56:59]
	v_mfma_f32_16x16x32_bf16 v[52:55], v[128:131], v[210:213], v[52:55]
	v_mfma_f32_16x16x32_bf16 v[44:47], v[136:139], v[210:213], v[44:47]
	v_mfma_f32_16x16x32_bf16 v[36:39], v[128:131], v[226:229], v[36:39]
	v_mfma_f32_16x16x32_bf16 v[28:31], v[136:139], v[226:229], v[28:31]
	v_mfma_f32_16x16x32_bf16 v[20:23], v[128:131], v[234:237], v[20:23]
	v_mfma_f32_16x16x32_bf16 v[12:15], v[136:139], v[234:237], v[12:15]
	v_mfma_f32_16x16x32_bf16 v[60:63], v[132:135], v[206:209], v[60:63]
	v_mfma_f32_16x16x32_bf16 v[56:59], v[140:143], v[206:209], v[56:59]
	v_mfma_f32_16x16x32_bf16 v[52:55], v[132:135], v[214:217], v[52:55]
	v_mfma_f32_16x16x32_bf16 v[44:47], v[140:143], v[214:217], v[44:47]
	v_mfma_f32_16x16x32_bf16 v[36:39], v[132:135], v[230:233], v[36:39]
	v_mfma_f32_16x16x32_bf16 v[28:31], v[140:143], v[230:233], v[28:31]
	v_mfma_f32_16x16x32_bf16 v[20:23], v[132:135], v[238:241], v[20:23]
	v_mfma_f32_16x16x32_bf16 v[12:15], v[140:143], v[238:241], v[12:15]
	v_mfma_f32_16x16x32_bf16 v[48:51], v[156:159], v[202:205], v[48:51]
	v_mfma_f32_16x16x32_bf16 v[40:43], v[168:171], v[202:205], v[40:43]
	v_mfma_f32_16x16x32_bf16 v[32:35], v[156:159], v[210:213], v[32:35]
	v_mfma_f32_16x16x32_bf16 v[24:27], v[168:171], v[210:213], v[24:27]
	v_mfma_f32_16x16x32_bf16 v[16:19], v[156:159], v[226:229], v[16:19]
	v_mfma_f32_16x16x32_bf16 v[8:11], v[168:171], v[226:229], v[8:11]
	v_mfma_f32_16x16x32_bf16 v[4:7], v[156:159], v[234:237], v[4:7]
	v_mfma_f32_16x16x32_bf16 v[0:3], v[168:171], v[234:237], v[0:3]
	v_mfma_f32_16x16x32_bf16 v[48:51], v[160:163], v[206:209], v[48:51]
	v_mfma_f32_16x16x32_bf16 v[40:43], v[178:181], v[206:209], v[40:43]
	v_mfma_f32_16x16x32_bf16 v[32:35], v[160:163], v[214:217], v[32:35]
	v_mfma_f32_16x16x32_bf16 v[24:27], v[178:181], v[214:217], v[24:27]
	v_mfma_f32_16x16x32_bf16 v[16:19], v[160:163], v[230:233], v[16:19]
	v_mfma_f32_16x16x32_bf16 v[8:11], v[178:181], v[230:233], v[8:11]
	v_mfma_f32_16x16x32_bf16 v[4:7], v[160:163], v[238:241], v[4:7]
	v_mfma_f32_16x16x32_bf16 v[0:3], v[178:181], v[238:241], v[0:3]
	s_barrier
	s_add_i32 s51, s51, 2
	s_add_u32 s49, s49, 0x100
	s_addc_u32 s50, s50, 0
	s_mov_b64 s[16:17], s[28:29]
	.p2align 6

; #define PG8_STAGE(bufoff, gbase, voff) do { _Pragma("unroll") for (int _i = 0; _i < 2; ++_i) \
;         __builtin_amdgcn_global_load_lds((const unsigned*)((const char*)(gbase) + (voff)[_i]), (LAS unsigned*)(lds + (bufoff) + ldsw + _i * 8192), 16, 0, 0); } while (0)
; #define PG8_WAIT_V(n) asm volatile("s_waitcnt vmcnt(" #n ")" ::: "memory")
; #define PG8_BAR __builtin_amdgcn_s_barrier()
; template <class Epi>
; __device__ __forceinline__ void gemm_phase(LAS unsigned char* lds, const Gemm g, const StaticOrder& S, const Epi& E, const int tid) {
;     ...
;                 for (int n = 0; n < 2; ++n) acc[a][b][m][n] = (f32x4){0.f, 0.f, 0.f, 0.f};
;     bf16x8 At[4][2], B0[2][2], B1[2][2];
;     const char* cA = (const char*)g.A + (size_t)cur.pm * tstepA + (size_t)cur.pn * pnoffA; const char* cB = (const char*)g.Bt + (size_t)cur.pn * tstepB;
;     PG8_STAGE(PG8_SB(0, 0), cB, voffB); PG8_STAGE(PG8_SB(0, 1), cB + hstepB, voffB); PG8_STAGE(PG8_SA(0, 0), cA, voffA); PG8_STAGE(PG8_SA(0, 1), cA + hstepA, voffA);
;     if (wr == 1) PG8_BAR;
;     PG8_WAIT_V(2); PG8_BAR;
;     PG8_STAGE(PG8_SB(1, 0), cB + kstep, voffB); PG8_STAGE(PG8_SA(1, 0), cA + kstepA, voffA); PG8_STAGE(PG8_SB(1, 1), cB + hstepB + kstep, voffB);
;     PG8_WAIT_V(6); PG8_BAR;
;     for (;;) {
;         const bool has_next = S.next(ui + 1, nxt);
;         const char* nA = has_next ? (const char*)g.A + (size_t)nxt.pm * tstepA + (size_t)nxt.pn * pnoffA : cA; const char* nB = has_next ? (const char*)g.Bt + (size_t)nxt.pn * tstepB : cB;
;         for (int t = 0; t < nt; t += 2) {
;             const bool last = (t == nt - 2);
;             const char* a1 = cA + (size_t)(t + 1) * kstepA;
;             const char* a2 = last ? nA : cA + (size_t)(t + 2) * kstepA; const char* b2 = last ? nB : cB + (size_t)(t + 2) * kstep;
;             const char* a3 = a2 + kstepA; const char* b3 = b2 + kstep;
;             PG8_LDB(B0, 0, 0); PG8_LDB(B1, 0, 1); PG8_SCHED; PG8_LDA(At, 0, 0); PG8_STAGE(PG8_SA(1, 1), a1 + hstepA, voffA);
;             PG8_WAIT_V(8); PG8_WAIT_L(0); PG8_BAR; PG8_MMA(0, 0, At, B0); PG8_MMA(0, 1, At, B1); PG8_BAR; PG8_SCHED;
;             PG8_LDA(At, 0, 1); PG8_STAGE(PG8_SB(0, 0), b2, voffB); PG8_STAGE(PG8_SB(0, 1), b2 + hstepB, voffB); PG8_STAGE(PG8_SA(0, 0), a2, voffA);
;             PG8_WAIT_V(8); PG8_WAIT_L(0); PG8_BAR; PG8_MMA(1, 0, At, B0); PG8_MMA(1, 1, At, B1); PG8_BAR; PG8_SCHED;
.LBB0_338:
	s_ashr_i32 s15, s14, 31
	s_lshl_b64 s[2:3], s[14:15], 19
	s_add_u32 s16, s24, s2
	s_addc_u32 s17, s25, s3
	s_and_b64 s[2:3], s[4:5], exec
	s_cselect_b32 s15, s17, s29
	s_cselect_b32 s51, s16, s28
	s_ashr_i32 s13, s12, 31
	s_lshl_b64 s[2:3], s[12:13], 19
	s_add_u32 s2, s20, s2
	s_addc_u32 s3, s21, s3
	s_and_b64 s[40:41], s[4:5], exec
	s_cselect_b32 s13, s3, s35
	s_cselect_b32 s52, s2, s34
	s_add_u32 s53, s34, 0x100
	s_addc_u32 s54, s35, 0
	s_mov_b32 s55, -2
	s_add_u32 s34, s28, 0x1000
	s_addc_u32 s35, s29, 0
	s_add_i32 s56, 0, 0x10000
	s_cmp_eq_u32 s55, 12
	s_cselect_b32 s43, s15, s35
	s_cselect_b32 s42, s51, s34
	v_add_u32_e32 v142, s56, v145
	s_cselect_b32 s41, s13, s54
	s_cselect_b32 s40, s52, s53
	s_add_i32 s57, 0, 0x14000
	ds_read_b128 v[158:161], v142
	ds_read_b128 v[162:165], v142 offset:1024
	ds_read_b128 v[166:169], v142 offset:2048
	ds_read_b128 v[170:173], v142 offset:3072
	v_add_u32_e32 v142, s57, v145
	ds_read_b128 v[194:197], v142
	ds_read_b128 v[202:205], v142 offset:1024
	ds_read_b128 v[206:209], v142 offset:2048
	ds_read_b128 v[210:213], v142 offset:3072
	v_lshl_add_u64 v[146:147], s[28:29], 0, v[138:139]
	s_add_i32 m0, s23, 0xc000
	ds_read_b128 v[214:217], v157
	ds_read_b128 v[226:229], v157 offset:1024
	ds_read_b128 v[230:233], v157 offset:2048
	ds_read_b128 v[234:237], v157 offset:3072
	ds_read_b128 v[238:241], v157 offset:4096
	ds_read_b128 v[242:245], v157 offset:5120
	ds_read_b128 v[246:249], v157 offset:6144
	ds_read_b128 v[178:181], v157 offset:7168
	global_load_lds_dwordx4 v[146:147], off
	v_lshl_add_u64 v[146:147], s[28:29], 0, v[140:141]
	s_add_i32 m0, s23, 0xe000
	s_nop 0
	global_load_lds_dwordx4 v[146:147], off
	s_waitcnt vmcnt(8)
	s_waitcnt lgkmcnt(0)
	s_barrier
	v_mfma_f32_16x16x32_bf16 v[124:127], v[158:161], v[214:217], 0
	v_mfma_f32_16x16x32_bf16 v[120:123], v[166:169], v[214:217], 0
	v_mfma_f32_16x16x32_bf16 v[116:119], v[158:161], v[230:233], 0
	v_mfma_f32_16x16x32_bf16 v[108:111], v[166:169], v[230:233], 0
	v_mfma_f32_16x16x32_bf16 v[100:103], v[158:161], v[238:241], 0
	v_mfma_f32_16x16x32_bf16 v[92:95], v[166:169], v[238:241], 0
	v_mfma_f32_16x16x32_bf16 v[84:87], v[158:161], v[246:249], 0
	v_mfma_f32_16x16x32_bf16 v[76:79], v[166:169], v[246:249], 0
	v_mfma_f32_16x16x32_bf16 v[124:127], v[162:165], v[226:229], v[124:127]
	v_mfma_f32_16x16x32_bf16 v[120:123], v[170:173], v[226:229], v[120:123]
	v_mfma_f32_16x16x32_bf16 v[116:119], v[162:165], v[234:237], v[116:119]
	v_mfma_f32_16x16x32_bf16 v[108:111], v[170:173], v[234:237], v[108:111]
	v_mfma_f32_16x16x32_bf16 v[100:103], v[162:165], v[242:245], v[100:103]
	v_mfma_f32_16x16x32_bf16 v[92:95], v[170:173], v[242:245], v[92:95]
	v_mfma_f32_16x16x32_bf16 v[84:87], v[162:165], v[178:181], v[84:87]
	v_mfma_f32_16x16x32_bf16 v[76:79], v[170:173], v[178:181], v[76:79]
	v_mfma_f32_16x16x32_bf16 v[112:115], v[194:197], v[214:217], 0
	v_mfma_f32_16x16x32_bf16 v[104:107], v[206:209], v[214:217], 0
	v_mfma_f32_16x16x32_bf16 v[96:99], v[194:197], v[230:233], 0
	v_mfma_f32_16x16x32_bf16 v[88:91], v[206:209], v[230:233], 0
	v_mfma_f32_16x16x32_bf16 v[80:83], v[194:197], v[238:241], 0
	v_mfma_f32_16x16x32_bf16 v[72:75], v[206:209], v[238:241], 0
	v_mfma_f32_16x16x32_bf16 v[68:71], v[194:197], v[246:249], 0
	v_mfma_f32_16x16x32_bf16 v[64:67], v[206:209], v[246:249], 0
	v_mfma_f32_16x16x32_bf16 v[112:115], v[202:205], v[226:229], v[112:115]
	v_mfma_f32_16x16x32_bf16 v[104:107], v[210:213], v[226:229], v[104:107]
	v_mfma_f32_16x16x32_bf16 v[96:99], v[202:205], v[234:237], v[96:99]
	v_mfma_f32_16x16x32_bf16 v[88:91], v[210:213], v[234:237], v[88:91]
	v_mfma_f32_16x16x32_bf16 v[80:83], v[202:205], v[242:245], v[80:83]
	v_mfma_f32_16x16x32_bf16 v[72:75], v[210:213], v[242:245], v[72:75]
	v_mfma_f32_16x16x32_bf16 v[68:71], v[202:205], v[178:181], v[68:71]
	v_mfma_f32_16x16x32_bf16 v[64:67], v[210:213], v[178:181], v[64:67]
	s_barrier
	s_add_i32 s28, s56, s22
	v_lshl_add_u64 v[146:147], s[40:41], 0, v[132:133]
	s_mov_b32 m0, s28
	ds_read_b128 v[178:181], v157 offset:16384
	ds_read_b128 v[214:217], v157 offset:17408
	ds_read_b128 v[226:229], v157 offset:18432
	ds_read_b128 v[230:233], v157 offset:19456
	ds_read_b128 v[234:237], v157 offset:20480
	ds_read_b128 v[238:241], v157 offset:21504
	ds_read_b128 v[242:245], v157 offset:22528
	ds_read_b128 v[246:249], v157 offset:23552
	global_load_lds_dwordx4 v[146:147], off
	s_add_i32 m0, s28, 0x2000
	s_add_u32 s28, s40, 0x40000
	v_lshl_add_u64 v[150:151], s[40:41], 0, v[128:129]
	s_addc_u32 s29, s41, 0
	s_add_i32 s56, s57, s22
	global_load_lds_dwordx4 v[150:151], off
	v_lshl_add_u64 v[154:155], s[28:29], 0, v[132:133]
	s_mov_b32 m0, s56
	v_lshl_add_u64 v[174:175], s[42:43], 0, v[130:131]
	global_load_lds_dwordx4 v[154:155], off
	v_lshl_add_u64 v[154:155], s[28:29], 0, v[128:129]
	s_add_i32 m0, s56, 0x2000
	s_nop 0
	global_load_lds_dwordx4 v[154:155], off
	v_lshl_add_u64 v[154:155], s[42:43], 0, v[134:135]
	s_mov_b32 m0, s23
	s_nop 0
	global_load_lds_dwordx4 v[154:155], off
	s_mov_b32 m0, s30
	s_nop 0
	global_load_lds_dwordx4 v[174:175], off
	s_waitcnt vmcnt(8)
	s_waitcnt lgkmcnt(0)
	s_barrier
; #define PG8_STAGE(bufoff, gbase, voff) do { _Pragma("unroll") for (int _i = 0; _i < 2; ++_i) \
;         __builtin_amdgcn_global_load_lds((const unsigned*)((const char*)(gbase) + (voff)[_i]), (LAS unsigned*)(lds + (bufoff) + ldsw + _i * 8192), 16, 0, 0); } while (0)
; #define PG8_LDA(dst, b, h) do { _Pragma("unroll") for (int m = 0; m < 4; ++m) _Pragma("unroll") for (int k = 0; k < 2; ++k) dst[m][k] = *(const LAS bf16x8*)(lds + PG8_SA(b, h) + aoff + m * 2048 + k * 1024); } while (0)
; #define PG8_LDB(dst, b, h) do { _Pragma("unroll") for (int n = 0; n < 2; ++n) _Pragma("unroll") for (int k = 0; k < 2; ++k) dst[n][k] = *(const LAS bf16x8*)(lds + PG8_SB(b, h) + boff + n * 2048 + k * 1024); } while (0)
; #define PG8_MMA(ai, bj, At, Bt) do { __builtin_amdgcn_s_setprio(1); _Pragma("unroll") for (int m = 0; m < 4; ++m) _Pragma("unroll") for (int n = 0; n < 2; ++n) _Pragma("unroll") for (int k = 0; k < 2; ++k) \
;         acc[ai][bj][m][n] = __builtin_amdgcn_mfma_f32_16x16x32_bf16(Bt[n][k], At[m][k], acc[ai][bj][m][n], 0, 0, 0); __builtin_amdgcn_s_setprio(0); } while (0)
; #define PG8_WAIT_V(n) asm volatile("s_waitcnt vmcnt(" #n ")" ::: "memory")
; #define PG8_WAIT_L(n) asm volatile("s_waitcnt lgkmcnt(" #n ")" ::: "memory")
; #define PG8_BAR __builtin_amdgcn_s_barrier()
; #define PG8_SCHED __builtin_amdgcn_sched_barrier(0)
; template <class Epi>
; __device__ __forceinline__ void gemm_phase(LAS unsigned char* lds, const Gemm g, const StaticOrder& S, const Epi& E, const int tid) {
;     ...
;             PG8_WAIT_V(8); PG8_WAIT_L(0); PG8_BAR; PG8_MMA(1, 0, At, B0); PG8_MMA(1, 1, At, B1); PG8_BAR; PG8_SCHED;
;             PG8_LDB(B0, 1, 0); PG8_LDB(B1, 1, 1); PG8_SCHED; PG8_LDA(At, 1, 0); PG8_STAGE(PG8_SA(0, 1), a2 + hstepA, voffA);
;             PG8_WAIT_V(8); PG8_WAIT_L(0); PG8_BAR; PG8_MMA(0, 0, At, B0); PG8_MMA(0, 1, At, B1); PG8_BAR; PG8_SCHED;
;             PG8_LDA(At, 1, 1); PG8_STAGE(PG8_SB(1, 0), b3, voffB); PG8_STAGE(PG8_SB(1, 1), b3 + hstepB, voffB); PG8_STAGE(PG8_SA(1, 0), a3, voffA);
	v_mfma_f32_16x16x32_bf16 v[60:63], v[158:161], v[178:181], 0
	v_mfma_f32_16x16x32_bf16 v[56:59], v[166:169], v[178:181], 0
	v_mfma_f32_16x16x32_bf16 v[52:55], v[158:161], v[226:229], 0
	v_mfma_f32_16x16x32_bf16 v[44:47], v[166:169], v[226:229], 0
	v_mfma_f32_16x16x32_bf16 v[36:39], v[158:161], v[234:237], 0
	v_mfma_f32_16x16x32_bf16 v[28:31], v[166:169], v[234:237], 0
	v_mfma_f32_16x16x32_bf16 v[20:23], v[158:161], v[242:245], 0
	v_mfma_f32_16x16x32_bf16 v[12:15], v[166:169], v[242:245], 0
	v_mfma_f32_16x16x32_bf16 v[60:63], v[162:165], v[214:217], v[60:63]
	v_mfma_f32_16x16x32_bf16 v[56:59], v[170:173], v[214:217], v[56:59]
	v_mfma_f32_16x16x32_bf16 v[52:55], v[162:165], v[230:233], v[52:55]
	v_mfma_f32_16x16x32_bf16 v[44:47], v[170:173], v[230:233], v[44:47]
	v_mfma_f32_16x16x32_bf16 v[36:39], v[162:165], v[238:241], v[36:39]
	v_mfma_f32_16x16x32_bf16 v[28:31], v[170:173], v[238:241], v[28:31]
	v_mfma_f32_16x16x32_bf16 v[20:23], v[162:165], v[246:249], v[20:23]
	v_mfma_f32_16x16x32_bf16 v[12:15], v[170:173], v[246:249], v[12:15]
	v_mfma_f32_16x16x32_bf16 v[48:51], v[194:197], v[178:181], 0
	v_mfma_f32_16x16x32_bf16 v[40:43], v[206:209], v[178:181], 0
	v_mfma_f32_16x16x32_bf16 v[32:35], v[194:197], v[226:229], 0
	v_mfma_f32_16x16x32_bf16 v[24:27], v[206:209], v[226:229], 0
	v_mfma_f32_16x16x32_bf16 v[16:19], v[194:197], v[234:237], 0
	v_mfma_f32_16x16x32_bf16 v[8:11], v[206:209], v[234:237], 0
	v_mfma_f32_16x16x32_bf16 v[4:7], v[194:197], v[242:245], 0
	v_mfma_f32_16x16x32_bf16 v[0:3], v[206:209], v[242:245], 0
	v_mfma_f32_16x16x32_bf16 v[48:51], v[202:205], v[214:217], v[48:51]
	v_mfma_f32_16x16x32_bf16 v[40:43], v[210:213], v[214:217], v[40:43]
	v_mfma_f32_16x16x32_bf16 v[32:35], v[202:205], v[230:233], v[32:35]
	v_mfma_f32_16x16x32_bf16 v[24:27], v[210:213], v[230:233], v[24:27]
	v_mfma_f32_16x16x32_bf16 v[16:19], v[202:205], v[238:241], v[16:19]
	v_mfma_f32_16x16x32_bf16 v[8:11], v[210:213], v[238:241], v[8:11]
	v_mfma_f32_16x16x32_bf16 v[4:7], v[202:205], v[246:249], v[4:7]
	v_mfma_f32_16x16x32_bf16 v[0:3], v[210:213], v[246:249], v[0:3]
	s_barrier
	s_add_i32 s56, 0, 0x18000
	v_add_u32_e32 v142, s56, v145
	s_add_i32 s57, 0, 0x1c000
	ds_read_b128 v[158:161], v142
	ds_read_b128 v[162:165], v142 offset:1024
	ds_read_b128 v[166:169], v142 offset:2048
	ds_read_b128 v[170:173], v142 offset:3072
	v_add_u32_e32 v142, s57, v145
	ds_read_b128 v[178:181], v142
	ds_read_b128 v[194:197], v142 offset:1024
	ds_read_b128 v[202:205], v142 offset:2048
	ds_read_b128 v[206:209], v142 offset:3072
	s_add_u32 s28, s42, 0x40000
	s_addc_u32 s29, s43, 0
	s_mov_b32 m0, s44
	v_lshl_add_u64 v[198:199], s[28:29], 0, v[134:135]
	ds_read_b128 v[210:213], v157 offset:32768
	ds_read_b128 v[214:217], v157 offset:33792
	ds_read_b128 v[226:229], v157 offset:34816
	ds_read_b128 v[230:233], v157 offset:35840
	ds_read_b128 v[234:237], v157 offset:36864
	ds_read_b128 v[238:241], v157 offset:37888
	ds_read_b128 v[242:245], v157 offset:38912
	ds_read_b128 v[246:249], v157 offset:39936
	global_load_lds_dwordx4 v[198:199], off
	v_lshl_add_u64 v[198:199], s[28:29], 0, v[130:131]
	s_mov_b32 m0, s45
	s_nop 0
	global_load_lds_dwordx4 v[198:199], off
	s_waitcnt vmcnt(8)
	s_waitcnt lgkmcnt(0)
	s_barrier
	v_mfma_f32_16x16x32_bf16 v[124:127], v[158:161], v[210:213], v[124:127]
	v_mfma_f32_16x16x32_bf16 v[120:123], v[166:169], v[210:213], v[120:123]
	v_mfma_f32_16x16x32_bf16 v[116:119], v[158:161], v[226:229], v[116:119]
	v_mfma_f32_16x16x32_bf16 v[108:111], v[166:169], v[226:229], v[108:111]
	v_mfma_f32_16x16x32_bf16 v[100:103], v[158:161], v[234:237], v[100:103]
	v_mfma_f32_16x16x32_bf16 v[92:95], v[166:169], v[234:237], v[92:95]
	v_mfma_f32_16x16x32_bf16 v[84:87], v[158:161], v[242:245], v[84:87]
	v_mfma_f32_16x16x32_bf16 v[76:79], v[166:169], v[242:245], v[76:79]
	v_mfma_f32_16x16x32_bf16 v[124:127], v[162:165], v[214:217], v[124:127]
	v_mfma_f32_16x16x32_bf16 v[120:123], v[170:173], v[214:217], v[120:123]
	v_mfma_f32_16x16x32_bf16 v[116:119], v[162:165], v[230:233], v[116:119]
	v_mfma_f32_16x16x32_bf16 v[108:111], v[170:173], v[230:233], v[108:111]
	v_mfma_f32_16x16x32_bf16 v[100:103], v[162:165], v[238:241], v[100:103]
	v_mfma_f32_16x16x32_bf16 v[92:95], v[170:173], v[238:241], v[92:95]
	v_mfma_f32_16x16x32_bf16 v[84:87], v[162:165], v[246:249], v[84:87]
	v_mfma_f32_16x16x32_bf16 v[76:79], v[170:173], v[246:249], v[76:79]
	v_mfma_f32_16x16x32_bf16 v[112:115], v[178:181], v[210:213], v[112:115]
	v_mfma_f32_16x16x32_bf16 v[104:107], v[202:205], v[210:213], v[104:107]
	v_mfma_f32_16x16x32_bf16 v[96:99], v[178:181], v[226:229], v[96:99]
	v_mfma_f32_16x16x32_bf16 v[88:91], v[202:205], v[226:229], v[88:91]
	v_mfma_f32_16x16x32_bf16 v[80:83], v[178:181], v[234:237], v[80:83]
	v_mfma_f32_16x16x32_bf16 v[72:75], v[202:205], v[234:237], v[72:75]
	v_mfma_f32_16x16x32_bf16 v[68:71], v[178:181], v[242:245], v[68:71]
	v_mfma_f32_16x16x32_bf16 v[64:67], v[202:205], v[242:245], v[64:67]
	v_mfma_f32_16x16x32_bf16 v[112:115], v[194:197], v[214:217], v[112:115]
	v_mfma_f32_16x16x32_bf16 v[104:107], v[206:209], v[214:217], v[104:107]
	v_mfma_f32_16x16x32_bf16 v[96:99], v[194:197], v[230:233], v[96:99]
	v_mfma_f32_16x16x32_bf16 v[88:91], v[206:209], v[230:233], v[88:91]
	v_mfma_f32_16x16x32_bf16 v[80:83], v[194:197], v[238:241], v[80:83]
	v_mfma_f32_16x16x32_bf16 v[72:75], v[206:209], v[238:241], v[72:75]
	v_mfma_f32_16x16x32_bf16 v[68:71], v[194:197], v[246:249], v[68:71]
	v_mfma_f32_16x16x32_bf16 v[64:67], v[206:209], v[246:249], v[64:67]
	s_barrier
; #define PG8_STAGE(bufoff, gbase, voff) do { _Pragma("unroll") for (int _i = 0; _i < 2; ++_i) \
;         __builtin_amdgcn_global_load_lds((const unsigned*)((const char*)(gbase) + (voff)[_i]), (LAS unsigned*)(lds + (bufoff) + ldsw + _i * 8192), 16, 0, 0); } while (0)
; #define PG8_LDA(dst, b, h) do { _Pragma("unroll") for (int m = 0; m < 4; ++m) _Pragma("unroll") for (int k = 0; k < 2; ++k) dst[m][k] = *(const LAS bf16x8*)(lds + PG8_SA(b, h) + aoff + m * 2048 + k * 1024); } while (0)
; #define PG8_MMA(ai, bj, At, Bt) do { __builtin_amdgcn_s_setprio(1); _Pragma("unroll") for (int m = 0; m < 4; ++m) _Pragma("unroll") for (int n = 0; n < 2; ++n) _Pragma("unroll") for (int k = 0; k < 2; ++k) \
;         acc[ai][bj][m][n] = __builtin_amdgcn_mfma_f32_16x16x32_bf16(Bt[n][k], At[m][k], acc[ai][bj][m][n], 0, 0, 0); __builtin_amdgcn_s_setprio(0); } while (0)
; #define PG8_WAIT_V(n) asm volatile("s_waitcnt vmcnt(" #n ")" ::: "memory")
; #define PG8_WAIT_L(n) asm volatile("s_waitcnt lgkmcnt(" #n ")" ::: "memory")
; #define PG8_BAR __builtin_amdgcn_s_barrier()
; #define PG8_SCHED __builtin_amdgcn_sched_barrier(0)
; template <class Epi>
; __device__ __forceinline__ void gemm_phase(LAS unsigned char* lds, const Gemm g, const StaticOrder& S, const Epi& E, const int tid) {
;     ...
;             PG8_LDA(At, 1, 1); PG8_STAGE(PG8_SB(1, 0), b3, voffB); PG8_STAGE(PG8_SB(1, 1), b3 + hstepB, voffB); PG8_STAGE(PG8_SA(1, 0), a3, voffA);
;             PG8_WAIT_V(8); PG8_WAIT_L(0); PG8_BAR; PG8_MMA(1, 0, At, B0); PG8_MMA(1, 1, At, B1); PG8_BAR; PG8_SCHED;
;         }
	s_add_i32 s28, s56, s22
	v_lshl_add_u64 v[146:147], v[146:147], 0, s[36:37]
	s_mov_b32 m0, s28
	ds_read_b128 v[210:213], v157 offset:49152
	ds_read_b128 v[214:217], v157 offset:50176
	ds_read_b128 v[226:229], v157 offset:51200
	ds_read_b128 v[230:233], v157 offset:52224
	ds_read_b128 v[234:237], v157 offset:53248
	ds_read_b128 v[238:241], v157 offset:54272
	ds_read_b128 v[242:245], v157 offset:55296
	ds_read_b128 v[246:249], v157 offset:56320
	global_load_lds_dwordx4 v[146:147], off
	s_add_i32 m0, s28, 0x2000
	s_add_u32 s28, s40, 0x40080
	v_lshl_add_u64 v[146:147], v[150:151], 0, s[36:37]
	s_addc_u32 s29, s41, 0
	s_add_i32 s40, s57, s22
	global_load_lds_dwordx4 v[146:147], off
	v_lshl_add_u64 v[146:147], s[28:29], 0, v[132:133]
	s_mov_b32 m0, s40
	s_nop 0
	global_load_lds_dwordx4 v[146:147], off
	v_lshl_add_u64 v[146:147], s[28:29], 0, v[128:129]
	s_add_i32 m0, s40, 0x2000
	s_nop 0
	global_load_lds_dwordx4 v[146:147], off
	v_lshl_add_u64 v[146:147], v[154:155], 0, s[76:77]
	s_mov_b32 m0, s46
	s_nop 0
	global_load_lds_dwordx4 v[146:147], off
	v_lshl_add_u64 v[146:147], v[174:175], 0, s[76:77]
	s_mov_b32 m0, s47
	s_nop 0
	global_load_lds_dwordx4 v[146:147], off
	s_waitcnt vmcnt(8)
	s_waitcnt lgkmcnt(0)
	s_barrier
	v_mfma_f32_16x16x32_bf16 v[60:63], v[158:161], v[210:213], v[60:63]
	v_mfma_f32_16x16x32_bf16 v[56:59], v[166:169], v[210:213], v[56:59]
	v_mfma_f32_16x16x32_bf16 v[52:55], v[158:161], v[226:229], v[52:55]
	v_mfma_f32_16x16x32_bf16 v[44:47], v[166:169], v[226:229], v[44:47]
	v_mfma_f32_16x16x32_bf16 v[36:39], v[158:161], v[234:237], v[36:39]
	v_mfma_f32_16x16x32_bf16 v[28:31], v[166:169], v[234:237], v[28:31]
	v_mfma_f32_16x16x32_bf16 v[20:23], v[158:161], v[242:245], v[20:23]
	v_mfma_f32_16x16x32_bf16 v[12:15], v[166:169], v[242:245], v[12:15]
	v_mfma_f32_16x16x32_bf16 v[60:63], v[162:165], v[214:217], v[60:63]
	v_mfma_f32_16x16x32_bf16 v[56:59], v[170:173], v[214:217], v[56:59]
	v_mfma_f32_16x16x32_bf16 v[52:55], v[162:165], v[230:233], v[52:55]
	v_mfma_f32_16x16x32_bf16 v[44:47], v[170:173], v[230:233], v[44:47]
	v_mfma_f32_16x16x32_bf16 v[36:39], v[162:165], v[238:241], v[36:39]
	v_mfma_f32_16x16x32_bf16 v[28:31], v[170:173], v[238:241], v[28:31]
	v_mfma_f32_16x16x32_bf16 v[20:23], v[162:165], v[246:249], v[20:23]
	v_mfma_f32_16x16x32_bf16 v[12:15], v[170:173], v[246:249], v[12:15]
	v_mfma_f32_16x16x32_bf16 v[48:51], v[178:181], v[210:213], v[48:51]
	v_mfma_f32_16x16x32_bf16 v[40:43], v[202:205], v[210:213], v[40:43]
	v_mfma_f32_16x16x32_bf16 v[32:35], v[178:181], v[226:229], v[32:35]
	v_mfma_f32_16x16x32_bf16 v[24:27], v[202:205], v[226:229], v[24:27]
	v_mfma_f32_16x16x32_bf16 v[16:19], v[178:181], v[234:237], v[16:19]
	v_mfma_f32_16x16x32_bf16 v[8:11], v[202:205], v[234:237], v[8:11]
	v_mfma_f32_16x16x32_bf16 v[4:7], v[178:181], v[242:245], v[4:7]
	v_mfma_f32_16x16x32_bf16 v[0:3], v[202:205], v[242:245], v[0:3]
	v_mfma_f32_16x16x32_bf16 v[48:51], v[194:197], v[214:217], v[48:51]
	v_mfma_f32_16x16x32_bf16 v[40:43], v[206:209], v[214:217], v[40:43]
	v_mfma_f32_16x16x32_bf16 v[32:35], v[194:197], v[230:233], v[32:35]
	v_mfma_f32_16x16x32_bf16 v[24:27], v[206:209], v[230:233], v[24:27]
	v_mfma_f32_16x16x32_bf16 v[16:19], v[194:197], v[238:241], v[16:19]
	v_mfma_f32_16x16x32_bf16 v[8:11], v[206:209], v[238:241], v[8:11]
	v_mfma_f32_16x16x32_bf16 v[4:7], v[194:197], v[246:249], v[4:7]
	v_mfma_f32_16x16x32_bf16 v[0:3], v[206:209], v[246:249], v[0:3]
	s_barrier
	s_add_i32 s55, s55, 2
	s_add_u32 s53, s53, 0x100
	s_addc_u32 s54, s54, 0
	s_mov_b64 s[28:29], s[34:35]
	.p2align 6

; template <class Epi>
; __device__ __forceinline__ void gemm_phase(LAS unsigned char* lds, const Gemm g, const StaticOrder& S, const Epi& E, const int tid) {
;     ...
;     f32x4 acc[2][2][4][2];
; #pragma unroll
;     for (int a = 0; a < 2; ++a)
; #pragma unroll
;         for (int b = 0; b < 2; ++b)
; #pragma unroll
;             for (int m = 0; m < 4; ++m)
; #pragma unroll
;                 for (int n = 0; n < 2; ++n) acc[a][b][m][n] = (f32x4){0.f, 0.f, 0.f, 0.f};
.LBB0_392:
	s_add_u32 s71, s2, s21
	s_addc_u32 s72, s3, 0
	s_add_u32 s73, s28, 0x100
	v_mov_b32_e32 v0, 0
	s_addc_u32 s75, s29, 0
	s_mov_b64 s[28:29], 0
	s_waitcnt lgkmcnt(0)
	v_mov_b64_e32 v[0:1], 0
	v_mov_b64_e32 v[2:3], 0
	v_mov_b64_e32 v[4:5], 0
	v_mov_b64_e32 v[6:7], 0
	v_mov_b64_e32 v[8:9], 0
	v_mov_b64_e32 v[10:11], 0
	v_mov_b64_e32 v[12:13], 0
	v_mov_b64_e32 v[14:15], 0
	v_mov_b64_e32 v[16:17], 0
	v_mov_b64_e32 v[18:19], 0
	v_mov_b64_e32 v[20:21], 0
	v_mov_b64_e32 v[22:23], 0
	v_mov_b64_e32 v[24:25], 0
	v_mov_b64_e32 v[26:27], 0
	v_mov_b64_e32 v[28:29], 0
	v_mov_b64_e32 v[30:31], 0
	v_mov_b64_e32 v[32:33], 0
	v_mov_b64_e32 v[34:35], 0
	v_mov_b64_e32 v[36:37], 0
	v_mov_b64_e32 v[38:39], 0
	v_mov_b64_e32 v[40:41], 0
	v_mov_b64_e32 v[42:43], 0
	v_mov_b64_e32 v[44:45], 0
	v_mov_b64_e32 v[46:47], 0
	v_mov_b64_e32 v[48:49], 0
	v_mov_b64_e32 v[50:51], 0
	v_mov_b64_e32 v[52:53], 0
	v_mov_b64_e32 v[54:55], 0
	v_mov_b64_e32 v[56:57], 0
	v_mov_b64_e32 v[58:59], 0
	v_mov_b64_e32 v[60:61], 0
	v_mov_b64_e32 v[62:63], 0
	v_mov_b64_e32 v[64:65], 0
	v_mov_b64_e32 v[66:67], 0
	v_mov_b64_e32 v[68:69], 0
	v_mov_b64_e32 v[70:71], 0
	v_mov_b64_e32 v[72:73], 0
	v_mov_b64_e32 v[74:75], 0
	v_mov_b64_e32 v[76:77], 0
	v_mov_b64_e32 v[78:79], 0
	v_mov_b64_e32 v[80:81], 0
	v_mov_b64_e32 v[82:83], 0
	v_mov_b64_e32 v[84:85], 0
	v_mov_b64_e32 v[86:87], 0
	v_mov_b64_e32 v[88:89], 0
	v_mov_b64_e32 v[90:91], 0
	v_mov_b64_e32 v[92:93], 0
	v_mov_b64_e32 v[94:95], 0
	v_mov_b64_e32 v[96:97], 0
	v_mov_b64_e32 v[98:99], 0
	v_mov_b64_e32 v[100:101], 0
	v_mov_b64_e32 v[102:103], 0
	v_mov_b64_e32 v[104:105], 0
	v_mov_b64_e32 v[106:107], 0
	v_mov_b64_e32 v[108:109], 0
	v_mov_b64_e32 v[110:111], 0
	v_mov_b64_e32 v[112:113], 0
	v_mov_b64_e32 v[114:115], 0
	v_mov_b64_e32 v[116:117], 0
	v_mov_b64_e32 v[118:119], 0
	v_mov_b64_e32 v[120:121], 0
	v_mov_b64_e32 v[122:123], 0
	v_mov_b64_e32 v[132:133], 0
	v_mov_b64_e32 v[134:135], 0
	.p2align 6

; template <class Epi>
; __device__ __forceinline__ void gemm_phase(LAS unsigned char* lds, const Gemm g, const StaticOrder& S, const Epi& E, const int tid) {
;     ...
;     f32x4 acc[2][2][4][2];
; #pragma unroll
;     for (int a = 0; a < 2; ++a)
; #pragma unroll
;         for (int b = 0; b < 2; ++b)
; #pragma unroll
;             for (int m = 0; m < 4; ++m)
; #pragma unroll
;                 for (int n = 0; n < 2; ++n) acc[a][b][m][n] = (f32x4){0.f, 0.f, 0.f, 0.f};
.LBB0_434:
	s_add_u32 s59, s2, 0x100
	s_addc_u32 s60, s3, 0
	s_add_u32 s2, s44, 0x800
	v_mov_b32_e32 v0, 0
	s_addc_u32 s3, s45, 0
	s_mov_b32 s44, 0
	v_mov_b64_e32 v[0:1], 0
	v_mov_b64_e32 v[2:3], 0
	v_mov_b64_e32 v[4:5], 0
	v_mov_b64_e32 v[6:7], 0
	v_mov_b64_e32 v[8:9], 0
	v_mov_b64_e32 v[10:11], 0
	v_mov_b64_e32 v[12:13], 0
	v_mov_b64_e32 v[14:15], 0
	v_mov_b64_e32 v[16:17], 0
	v_mov_b64_e32 v[18:19], 0
	v_mov_b64_e32 v[20:21], 0
	v_mov_b64_e32 v[22:23], 0
	v_mov_b64_e32 v[24:25], 0
	v_mov_b64_e32 v[26:27], 0
	v_mov_b64_e32 v[28:29], 0
	v_mov_b64_e32 v[30:31], 0
	v_mov_b64_e32 v[32:33], 0
	v_mov_b64_e32 v[34:35], 0
	v_mov_b64_e32 v[36:37], 0
	v_mov_b64_e32 v[38:39], 0
	v_mov_b64_e32 v[40:41], 0
	v_mov_b64_e32 v[42:43], 0
	v_mov_b64_e32 v[44:45], 0
	v_mov_b64_e32 v[46:47], 0
	v_mov_b64_e32 v[48:49], 0
	v_mov_b64_e32 v[50:51], 0
	v_mov_b64_e32 v[52:53], 0
	v_mov_b64_e32 v[54:55], 0
	v_mov_b64_e32 v[56:57], 0
	v_mov_b64_e32 v[58:59], 0
	v_mov_b64_e32 v[60:61], 0
	v_mov_b64_e32 v[62:63], 0
	v_mov_b64_e32 v[64:65], 0
	v_mov_b64_e32 v[66:67], 0
	v_mov_b64_e32 v[68:69], 0
	v_mov_b64_e32 v[70:71], 0
	v_mov_b64_e32 v[72:73], 0
	v_mov_b64_e32 v[74:75], 0
	v_mov_b64_e32 v[76:77], 0
	v_mov_b64_e32 v[78:79], 0
	v_mov_b64_e32 v[80:81], 0
	v_mov_b64_e32 v[82:83], 0
	v_mov_b64_e32 v[84:85], 0
	v_mov_b64_e32 v[86:87], 0
	v_mov_b64_e32 v[88:89], 0
	v_mov_b64_e32 v[90:91], 0
	v_mov_b64_e32 v[92:93], 0
	v_mov_b64_e32 v[94:95], 0
	v_mov_b64_e32 v[96:97], 0
	v_mov_b64_e32 v[98:99], 0
	v_mov_b64_e32 v[100:101], 0
	v_mov_b64_e32 v[102:103], 0
	v_mov_b64_e32 v[104:105], 0
	v_mov_b64_e32 v[106:107], 0
	v_mov_b64_e32 v[108:109], 0
	v_mov_b64_e32 v[110:111], 0
	v_mov_b64_e32 v[112:113], 0
	v_mov_b64_e32 v[114:115], 0
	v_mov_b64_e32 v[116:117], 0
	v_mov_b64_e32 v[118:119], 0
	v_mov_b64_e32 v[120:121], 0
	v_mov_b64_e32 v[122:123], 0
	v_mov_b64_e32 v[124:125], 0
	v_mov_b64_e32 v[126:127], 0
	.p2align 6

; __device__ __forceinline__ f32x4 gload16(const void* p) { f32x4 v; asm volatile("global_load_dwordx4 %0, %1, off" : "=v"(v) : "v"(p) : "memory"); return v; }
; __device__ __forceinline__ void rows_rstd_issue(const float* SS, int row0, int fq, f32x4 (&p)[8]) {
; #pragma unroll
;     for (int i = 0; i < 8; ++i) p[i] = gload16(SS + (size_t)(row0 + (i >> 2) * HALF + (i & 3) * 16) * 16 + fq * 4);
; }
; template <class Epi>
; __device__ __forceinline__ void gemm_phase(LAS unsigned char* lds, const Gemm g, const StaticOrder& S, const Epi& E, const int tid) {
;     ...
;                 for (int n = 0; n < 2; ++n) acc[a][b][m][n] = (f32x4){0.f, 0.f, 0.f, 0.f};
;     bf16x8 At[4][2], B0[2][2], B1[2][2];
;     const char* cA = (const char*)g.A + (size_t)cur.pm * tstepA + (size_t)cur.pn * pnoffA; const char* cB = (const char*)g.Bt + (size_t)cur.pn * tstepB;
;     PG8_STAGE(PG8_SB(0, 0), cB, voffB); PG8_STAGE(PG8_SB(0, 1), cB + hstepB, voffB); PG8_STAGE(PG8_SA(0, 0), cA, voffA); PG8_STAGE(PG8_SA(0, 1), cA + hstepA, voffA);
;     if (wr == 1) PG8_BAR;
;     PG8_WAIT_V(2); PG8_BAR;
;     PG8_STAGE(PG8_SB(1, 0), cB + kstep, voffB); PG8_STAGE(PG8_SA(1, 0), cA + kstepA, voffA); PG8_STAGE(PG8_SB(1, 1), cB + hstepB + kstep, voffB);
;     PG8_WAIT_V(6); PG8_BAR;
;     for (;;) {
;         const bool has_next = S.next(ui + 1, nxt);
;         const char* nA = has_next ? (const char*)g.A + (size_t)nxt.pm * tstepA + (size_t)nxt.pn * pnoffA : cA; const char* nB = has_next ? (const char*)g.Bt + (size_t)nxt.pn * tstepB : cB;
;         for (int t = 0; t < nt; t += 2) {
;             const bool last = (t == nt - 2);
;             const char* a1 = cA + (size_t)(t + 1) * kstepA;
;             const char* a2 = last ? nA : cA + (size_t)(t + 2) * kstepA; const char* b2 = last ? nB : cB + (size_t)(t + 2) * kstep;
;             const char* a3 = a2 + kstepA; const char* b3 = b2 + kstep;
;             PG8_LDB(B0, 0, 0); PG8_LDB(B1, 0, 1); PG8_SCHED; PG8_LDA(At, 0, 0); PG8_STAGE(PG8_SA(1, 1), a1 + hstepA, voffA);
;             PG8_WAIT_V(8); PG8_WAIT_L(0); PG8_BAR; PG8_MMA(0, 0, At, B0); PG8_MMA(0, 1, At, B1); PG8_BAR; PG8_SCHED;
;             PG8_LDA(At, 0, 1); PG8_STAGE(PG8_SB(0, 0), b2, voffB); PG8_STAGE(PG8_SB(0, 1), b2 + hstepB, voffB); PG8_STAGE(PG8_SA(0, 0), a2, voffA);
;             PG8_WAIT_V(8); PG8_WAIT_L(0); PG8_BAR; PG8_MMA(1, 0, At, B0); PG8_MMA(1, 1, At, B1); PG8_BAR; PG8_SCHED;
.LBB0_452:
	s_ashr_i32 s13, s12, 31
	s_lshl_b64 s[14:15], s[12:13], 19
	s_add_u32 s14, s24, s14
	s_addc_u32 s15, s25, s15
	s_and_b64 s[16:17], s[4:5], exec
	s_cselect_b32 s13, s15, s3
	s_cselect_b32 s51, s14, s2
	s_ashr_i32 s11, s10, 31
	s_lshl_b64 s[16:17], s[10:11], 19
	s_add_u32 s16, s20, s16
	s_addc_u32 s17, s21, s17
	s_and_b64 s[34:35], s[4:5], exec
	s_cselect_b32 s11, s17, s29
	s_cselect_b32 s52, s16, s28
	s_add_u32 s53, s28, 0x100
	s_addc_u32 s54, s29, 0
	s_mov_b32 s55, -2
	s_add_u32 s28, s2, 0x1000
	s_addc_u32 s29, s3, 0
	s_add_i32 s56, 0, 0x10000
	s_cmp_eq_u32 s55, 12
	s_cselect_b32 s41, s13, s29
	s_cselect_b32 s40, s51, s28
	v_add_u32_e32 v145, s56, v143
	s_cselect_b32 s35, s11, s54
	s_cselect_b32 s34, s52, s53
	s_add_i32 s57, 0, 0x14000
	ds_read_b128 v[146:149], v145
	ds_read_b128 v[150:153], v145 offset:1024
	ds_read_b128 v[154:157], v145 offset:2048
	ds_read_b128 v[158:161], v145 offset:3072
	v_add_u32_e32 v145, s57, v143
	ds_read_b128 v[162:165], v145
	ds_read_b128 v[166:169], v145 offset:1024
	ds_read_b128 v[170:173], v145 offset:2048
	ds_read_b128 v[194:197], v145 offset:3072
	v_lshl_add_u64 v[174:175], s[2:3], 0, v[138:139]
	s_add_i32 m0, s23, 0xc000
	ds_read_b128 v[202:205], v144
	ds_read_b128 v[206:209], v144 offset:1024
	ds_read_b128 v[210:213], v144 offset:2048
	ds_read_b128 v[214:217], v144 offset:3072
	ds_read_b128 v[226:229], v144 offset:4096
	ds_read_b128 v[230:233], v144 offset:5120
	ds_read_b128 v[234:237], v144 offset:6144
	ds_read_b128 v[238:241], v144 offset:7168
	global_load_lds_dwordx4 v[174:175], off
	v_lshl_add_u64 v[174:175], s[2:3], 0, v[140:141]
	s_add_i32 m0, s23, 0xe000
	s_nop 0
	global_load_lds_dwordx4 v[174:175], off
	s_waitcnt vmcnt(8)
	s_waitcnt lgkmcnt(0)
	s_barrier
	v_mfma_f32_16x16x32_bf16 v[124:127], v[146:149], v[202:205], 0
	v_mfma_f32_16x16x32_bf16 v[116:119], v[154:157], v[202:205], 0
	v_mfma_f32_16x16x32_bf16 v[108:111], v[146:149], v[210:213], 0
	v_mfma_f32_16x16x32_bf16 v[100:103], v[154:157], v[210:213], 0
	v_mfma_f32_16x16x32_bf16 v[92:95], v[146:149], v[226:229], 0
	v_mfma_f32_16x16x32_bf16 v[84:87], v[154:157], v[226:229], 0
	v_mfma_f32_16x16x32_bf16 v[76:79], v[146:149], v[234:237], 0
	v_mfma_f32_16x16x32_bf16 v[68:71], v[154:157], v[234:237], 0
	v_mfma_f32_16x16x32_bf16 v[124:127], v[150:153], v[206:209], v[124:127]
	v_mfma_f32_16x16x32_bf16 v[116:119], v[158:161], v[206:209], v[116:119]
	v_mfma_f32_16x16x32_bf16 v[108:111], v[150:153], v[214:217], v[108:111]
	v_mfma_f32_16x16x32_bf16 v[100:103], v[158:161], v[214:217], v[100:103]
	v_mfma_f32_16x16x32_bf16 v[92:95], v[150:153], v[230:233], v[92:95]
	v_mfma_f32_16x16x32_bf16 v[84:87], v[158:161], v[230:233], v[84:87]
	v_mfma_f32_16x16x32_bf16 v[76:79], v[150:153], v[238:241], v[76:79]
	v_mfma_f32_16x16x32_bf16 v[68:71], v[158:161], v[238:241], v[68:71]
	v_mfma_f32_16x16x32_bf16 v[120:123], v[162:165], v[202:205], 0
	v_mfma_f32_16x16x32_bf16 v[112:115], v[170:173], v[202:205], 0
	v_mfma_f32_16x16x32_bf16 v[104:107], v[162:165], v[210:213], 0
	v_mfma_f32_16x16x32_bf16 v[96:99], v[170:173], v[210:213], 0
	v_mfma_f32_16x16x32_bf16 v[88:91], v[162:165], v[226:229], 0
	v_mfma_f32_16x16x32_bf16 v[80:83], v[170:173], v[226:229], 0
	v_mfma_f32_16x16x32_bf16 v[72:75], v[162:165], v[234:237], 0
	v_mfma_f32_16x16x32_bf16 v[64:67], v[170:173], v[234:237], 0
	v_mfma_f32_16x16x32_bf16 v[120:123], v[166:169], v[206:209], v[120:123]
	v_mfma_f32_16x16x32_bf16 v[112:115], v[194:197], v[206:209], v[112:115]
	v_mfma_f32_16x16x32_bf16 v[104:107], v[166:169], v[214:217], v[104:107]
	v_mfma_f32_16x16x32_bf16 v[96:99], v[194:197], v[214:217], v[96:99]
	v_mfma_f32_16x16x32_bf16 v[88:91], v[166:169], v[230:233], v[88:91]
	v_mfma_f32_16x16x32_bf16 v[80:83], v[194:197], v[230:233], v[80:83]
	v_mfma_f32_16x16x32_bf16 v[72:75], v[166:169], v[238:241], v[72:75]
	v_mfma_f32_16x16x32_bf16 v[64:67], v[194:197], v[238:241], v[64:67]
	s_barrier
	s_lshl_b32 s100, s50, 14
	s_add_u32 s100, s82, s100
	s_addc_u32 s101, s83, 0
	s_lshl_b32 m0, s22, 1
	s_add_i32 m0, m0, 0x20800
	s_nop 0
	global_load_lds_dwordx4 v193, s[100:101]
	global_load_lds_dwordx4 v193, s[100:101] offset:1024
	s_add_i32 s2, s56, s22
	v_lshl_add_u64 v[174:175], s[34:35], 0, v[176:177]
	s_mov_b32 m0, s2
	ds_read_b128 v[202:205], v144 offset:16384
	ds_read_b128 v[206:209], v144 offset:17408
	ds_read_b128 v[210:213], v144 offset:18432
	ds_read_b128 v[214:217], v144 offset:19456
	ds_read_b128 v[226:229], v144 offset:20480
	ds_read_b128 v[230:233], v144 offset:21504
	ds_read_b128 v[234:237], v144 offset:22528
	ds_read_b128 v[238:241], v144 offset:23552
	global_load_lds_dwordx4 v[174:175], off
	s_add_i32 m0, s2, 0x2000
	s_add_u32 s2, s34, 0x40000
	v_lshl_add_u64 v[178:179], s[34:35], 0, v[128:129]
	s_addc_u32 s3, s35, 0
	s_add_i32 s56, s57, s22
	global_load_lds_dwordx4 v[178:179], off
	v_lshl_add_u64 v[180:181], s[2:3], 0, v[176:177]
	s_mov_b32 m0, s56
	v_lshl_add_u64 v[198:199], s[40:41], 0, v[130:131]
	global_load_lds_dwordx4 v[180:181], off
	v_lshl_add_u64 v[180:181], s[2:3], 0, v[128:129]
	s_add_i32 m0, s56, 0x2000
	s_nop 0
	global_load_lds_dwordx4 v[180:181], off
	v_lshl_add_u64 v[180:181], s[40:41], 0, v[132:133]
	s_mov_b32 m0, s23
	s_nop 0
	global_load_lds_dwordx4 v[180:181], off
	s_mov_b32 m0, s30
	s_nop 0
	global_load_lds_dwordx4 v[198:199], off
	s_waitcnt vmcnt(8)
	s_waitcnt lgkmcnt(0)
	s_barrier
; #define PG8_STAGE(bufoff, gbase, voff) do { _Pragma("unroll") for (int _i = 0; _i < 2; ++_i) \
;         __builtin_amdgcn_global_load_lds((const unsigned*)((const char*)(gbase) + (voff)[_i]), (LAS unsigned*)(lds + (bufoff) + ldsw + _i * 8192), 16, 0, 0); } while (0)
; #define PG8_LDA(dst, b, h) do { _Pragma("unroll") for (int m = 0; m < 4; ++m) _Pragma("unroll") for (int k = 0; k < 2; ++k) dst[m][k] = *(const LAS bf16x8*)(lds + PG8_SA(b, h) + aoff + m * 2048 + k * 1024); } while (0)
; #define PG8_LDB(dst, b, h) do { _Pragma("unroll") for (int n = 0; n < 2; ++n) _Pragma("unroll") for (int k = 0; k < 2; ++k) dst[n][k] = *(const LAS bf16x8*)(lds + PG8_SB(b, h) + boff + n * 2048 + k * 1024); } while (0)
; #define PG8_MMA(ai, bj, At, Bt) do { __builtin_amdgcn_s_setprio(1); _Pragma("unroll") for (int m = 0; m < 4; ++m) _Pragma("unroll") for (int n = 0; n < 2; ++n) _Pragma("unroll") for (int k = 0; k < 2; ++k) \
;         acc[ai][bj][m][n] = __builtin_amdgcn_mfma_f32_16x16x32_bf16(Bt[n][k], At[m][k], acc[ai][bj][m][n], 0, 0, 0); __builtin_amdgcn_s_setprio(0); } while (0)
; #define PG8_WAIT_V(n) asm volatile("s_waitcnt vmcnt(" #n ")" ::: "memory")
; #define PG8_WAIT_L(n) asm volatile("s_waitcnt lgkmcnt(" #n ")" ::: "memory")
; #define PG8_BAR __builtin_amdgcn_s_barrier()
; #define PG8_SCHED __builtin_amdgcn_sched_barrier(0)
; template <class Epi>
; __device__ __forceinline__ void gemm_phase(LAS unsigned char* lds, const Gemm g, const StaticOrder& S, const Epi& E, const int tid) {
;     ...
;             PG8_WAIT_V(8); PG8_WAIT_L(0); PG8_BAR; PG8_MMA(1, 0, At, B0); PG8_MMA(1, 1, At, B1); PG8_BAR; PG8_SCHED;
;             PG8_LDB(B0, 1, 0); PG8_LDB(B1, 1, 1); PG8_SCHED; PG8_LDA(At, 1, 0); PG8_STAGE(PG8_SA(0, 1), a2 + hstepA, voffA);
;             PG8_WAIT_V(8); PG8_WAIT_L(0); PG8_BAR; PG8_MMA(0, 0, At, B0); PG8_MMA(0, 1, At, B1); PG8_BAR; PG8_SCHED;
;             PG8_LDA(At, 1, 1); PG8_STAGE(PG8_SB(1, 0), b3, voffB); PG8_STAGE(PG8_SB(1, 1), b3 + hstepB, voffB); PG8_STAGE(PG8_SA(1, 0), a3, voffA);
	v_mfma_f32_16x16x32_bf16 v[60:63], v[146:149], v[202:205], 0
	v_mfma_f32_16x16x32_bf16 v[52:55], v[154:157], v[202:205], 0
	v_mfma_f32_16x16x32_bf16 v[44:47], v[146:149], v[210:213], 0
	v_mfma_f32_16x16x32_bf16 v[36:39], v[154:157], v[210:213], 0
	v_mfma_f32_16x16x32_bf16 v[28:31], v[146:149], v[226:229], 0
	v_mfma_f32_16x16x32_bf16 v[20:23], v[154:157], v[226:229], 0
	v_mfma_f32_16x16x32_bf16 v[12:15], v[146:149], v[234:237], 0
	v_mfma_f32_16x16x32_bf16 v[4:7], v[154:157], v[234:237], 0
	v_mfma_f32_16x16x32_bf16 v[60:63], v[150:153], v[206:209], v[60:63]
	v_mfma_f32_16x16x32_bf16 v[52:55], v[158:161], v[206:209], v[52:55]
	v_mfma_f32_16x16x32_bf16 v[44:47], v[150:153], v[214:217], v[44:47]
	v_mfma_f32_16x16x32_bf16 v[36:39], v[158:161], v[214:217], v[36:39]
	v_mfma_f32_16x16x32_bf16 v[28:31], v[150:153], v[230:233], v[28:31]
	v_mfma_f32_16x16x32_bf16 v[20:23], v[158:161], v[230:233], v[20:23]
	v_mfma_f32_16x16x32_bf16 v[12:15], v[150:153], v[238:241], v[12:15]
	v_mfma_f32_16x16x32_bf16 v[4:7], v[158:161], v[238:241], v[4:7]
	v_mfma_f32_16x16x32_bf16 v[56:59], v[162:165], v[202:205], 0
	v_mfma_f32_16x16x32_bf16 v[48:51], v[170:173], v[202:205], 0
	v_mfma_f32_16x16x32_bf16 v[40:43], v[162:165], v[210:213], 0
	v_mfma_f32_16x16x32_bf16 v[32:35], v[170:173], v[210:213], 0
	v_mfma_f32_16x16x32_bf16 v[24:27], v[162:165], v[226:229], 0
	v_mfma_f32_16x16x32_bf16 v[16:19], v[170:173], v[226:229], 0
	v_mfma_f32_16x16x32_bf16 v[8:11], v[162:165], v[234:237], 0
	v_mfma_f32_16x16x32_bf16 v[0:3], v[170:173], v[234:237], 0
	v_mfma_f32_16x16x32_bf16 v[56:59], v[166:169], v[206:209], v[56:59]
	v_mfma_f32_16x16x32_bf16 v[48:51], v[194:197], v[206:209], v[48:51]
	v_mfma_f32_16x16x32_bf16 v[40:43], v[166:169], v[214:217], v[40:43]
	v_mfma_f32_16x16x32_bf16 v[32:35], v[194:197], v[214:217], v[32:35]
	v_mfma_f32_16x16x32_bf16 v[24:27], v[166:169], v[230:233], v[24:27]
	v_mfma_f32_16x16x32_bf16 v[16:19], v[194:197], v[230:233], v[16:19]
	v_mfma_f32_16x16x32_bf16 v[8:11], v[166:169], v[238:241], v[8:11]
	v_mfma_f32_16x16x32_bf16 v[0:3], v[194:197], v[238:241], v[0:3]
	s_barrier
	s_add_i32 s56, 0, 0x18000
	v_add_u32_e32 v145, s56, v143
	s_add_i32 s57, 0, 0x1c000
	ds_read_b128 v[146:149], v145
	ds_read_b128 v[150:153], v145 offset:1024
	ds_read_b128 v[154:157], v145 offset:2048
	ds_read_b128 v[158:161], v145 offset:3072
	v_add_u32_e32 v145, s57, v143
	ds_read_b128 v[162:165], v145
	ds_read_b128 v[166:169], v145 offset:1024
	ds_read_b128 v[170:173], v145 offset:2048
	ds_read_b128 v[194:197], v145 offset:3072
	s_add_u32 s2, s40, 0x40000
	s_addc_u32 s3, s41, 0
	s_mov_b32 m0, s42
	v_lshl_add_u64 v[218:219], s[2:3], 0, v[132:133]
	ds_read_b128 v[202:205], v144 offset:32768
	ds_read_b128 v[206:209], v144 offset:33792
	ds_read_b128 v[210:213], v144 offset:34816
	ds_read_b128 v[214:217], v144 offset:35840
	ds_read_b128 v[226:229], v144 offset:36864
	ds_read_b128 v[230:233], v144 offset:37888
	ds_read_b128 v[234:237], v144 offset:38912
	ds_read_b128 v[238:241], v144 offset:39936
	global_load_lds_dwordx4 v[218:219], off
	v_lshl_add_u64 v[218:219], s[2:3], 0, v[130:131]
	s_mov_b32 m0, s43
	s_nop 0
	global_load_lds_dwordx4 v[218:219], off
	s_waitcnt vmcnt(8)
	s_waitcnt lgkmcnt(0)
	s_barrier
	v_mfma_f32_16x16x32_bf16 v[124:127], v[146:149], v[202:205], v[124:127]
	v_mfma_f32_16x16x32_bf16 v[116:119], v[154:157], v[202:205], v[116:119]
	v_mfma_f32_16x16x32_bf16 v[108:111], v[146:149], v[210:213], v[108:111]
	v_mfma_f32_16x16x32_bf16 v[100:103], v[154:157], v[210:213], v[100:103]
	v_mfma_f32_16x16x32_bf16 v[92:95], v[146:149], v[226:229], v[92:95]
	v_mfma_f32_16x16x32_bf16 v[84:87], v[154:157], v[226:229], v[84:87]
	v_mfma_f32_16x16x32_bf16 v[76:79], v[146:149], v[234:237], v[76:79]
	v_mfma_f32_16x16x32_bf16 v[68:71], v[154:157], v[234:237], v[68:71]
	v_mfma_f32_16x16x32_bf16 v[124:127], v[150:153], v[206:209], v[124:127]
	v_mfma_f32_16x16x32_bf16 v[116:119], v[158:161], v[206:209], v[116:119]
	v_mfma_f32_16x16x32_bf16 v[108:111], v[150:153], v[214:217], v[108:111]
	v_mfma_f32_16x16x32_bf16 v[100:103], v[158:161], v[214:217], v[100:103]
	v_mfma_f32_16x16x32_bf16 v[92:95], v[150:153], v[230:233], v[92:95]
	v_mfma_f32_16x16x32_bf16 v[84:87], v[158:161], v[230:233], v[84:87]
	v_mfma_f32_16x16x32_bf16 v[76:79], v[150:153], v[238:241], v[76:79]
	v_mfma_f32_16x16x32_bf16 v[68:71], v[158:161], v[238:241], v[68:71]
	v_mfma_f32_16x16x32_bf16 v[120:123], v[162:165], v[202:205], v[120:123]
	v_mfma_f32_16x16x32_bf16 v[112:115], v[170:173], v[202:205], v[112:115]
	v_mfma_f32_16x16x32_bf16 v[104:107], v[162:165], v[210:213], v[104:107]
	v_mfma_f32_16x16x32_bf16 v[96:99], v[170:173], v[210:213], v[96:99]
	v_mfma_f32_16x16x32_bf16 v[88:91], v[162:165], v[226:229], v[88:91]
	v_mfma_f32_16x16x32_bf16 v[80:83], v[170:173], v[226:229], v[80:83]
	v_mfma_f32_16x16x32_bf16 v[72:75], v[162:165], v[234:237], v[72:75]
	v_mfma_f32_16x16x32_bf16 v[64:67], v[170:173], v[234:237], v[64:67]
	v_mfma_f32_16x16x32_bf16 v[120:123], v[166:169], v[206:209], v[120:123]
	v_mfma_f32_16x16x32_bf16 v[112:115], v[194:197], v[206:209], v[112:115]
	v_mfma_f32_16x16x32_bf16 v[104:107], v[166:169], v[214:217], v[104:107]
	v_mfma_f32_16x16x32_bf16 v[96:99], v[194:197], v[214:217], v[96:99]
	v_mfma_f32_16x16x32_bf16 v[88:91], v[166:169], v[230:233], v[88:91]
	v_mfma_f32_16x16x32_bf16 v[80:83], v[194:197], v[230:233], v[80:83]
	v_mfma_f32_16x16x32_bf16 v[72:75], v[166:169], v[238:241], v[72:75]
	v_mfma_f32_16x16x32_bf16 v[64:67], v[194:197], v[238:241], v[64:67]
	s_barrier
; #define PG8_STAGE(bufoff, gbase, voff) do { _Pragma("unroll") for (int _i = 0; _i < 2; ++_i) \
;         __builtin_amdgcn_global_load_lds((const unsigned*)((const char*)(gbase) + (voff)[_i]), (LAS unsigned*)(lds + (bufoff) + ldsw + _i * 8192), 16, 0, 0); } while (0)
; #define PG8_LDA(dst, b, h) do { _Pragma("unroll") for (int m = 0; m < 4; ++m) _Pragma("unroll") for (int k = 0; k < 2; ++k) dst[m][k] = *(const LAS bf16x8*)(lds + PG8_SA(b, h) + aoff + m * 2048 + k * 1024); } while (0)
; #define PG8_MMA(ai, bj, At, Bt) do { __builtin_amdgcn_s_setprio(1); _Pragma("unroll") for (int m = 0; m < 4; ++m) _Pragma("unroll") for (int n = 0; n < 2; ++n) _Pragma("unroll") for (int k = 0; k < 2; ++k) \
;         acc[ai][bj][m][n] = __builtin_amdgcn_mfma_f32_16x16x32_bf16(Bt[n][k], At[m][k], acc[ai][bj][m][n], 0, 0, 0); __builtin_amdgcn_s_setprio(0); } while (0)
; #define PG8_WAIT_V(n) asm volatile("s_waitcnt vmcnt(" #n ")" ::: "memory")
; #define PG8_WAIT_L(n) asm volatile("s_waitcnt lgkmcnt(" #n ")" ::: "memory")
; #define PG8_BAR __builtin_amdgcn_s_barrier()
; #define PG8_SCHED __builtin_amdgcn_sched_barrier(0)
; template <class Epi>
; __device__ __forceinline__ void gemm_phase(LAS unsigned char* lds, const Gemm g, const StaticOrder& S, const Epi& E, const int tid) {
;     ...
;             PG8_LDA(At, 1, 1); PG8_STAGE(PG8_SB(1, 0), b3, voffB); PG8_STAGE(PG8_SB(1, 1), b3 + hstepB, voffB); PG8_STAGE(PG8_SA(1, 0), a3, voffA);
;             PG8_WAIT_V(8); PG8_WAIT_L(0); PG8_BAR; PG8_MMA(1, 0, At, B0); PG8_MMA(1, 1, At, B1); PG8_BAR; PG8_SCHED;
;         }
	s_add_i32 s2, s56, s22
	v_lshl_add_u64 v[174:175], v[174:175], 0, s[36:37]
	s_mov_b32 m0, s2
	ds_read_b128 v[202:205], v144 offset:49152
	ds_read_b128 v[206:209], v144 offset:50176
	ds_read_b128 v[210:213], v144 offset:51200
	ds_read_b128 v[214:217], v144 offset:52224
	ds_read_b128 v[226:229], v144 offset:53248
	ds_read_b128 v[230:233], v144 offset:54272
	ds_read_b128 v[234:237], v144 offset:55296
	ds_read_b128 v[238:241], v144 offset:56320
	global_load_lds_dwordx4 v[174:175], off
	s_add_i32 m0, s2, 0x2000
	s_add_u32 s2, s34, 0x40080
	v_lshl_add_u64 v[174:175], v[178:179], 0, s[36:37]
	s_addc_u32 s3, s35, 0
	s_add_i32 s34, s57, s22
	global_load_lds_dwordx4 v[174:175], off
	v_lshl_add_u64 v[174:175], s[2:3], 0, v[176:177]
	s_mov_b32 m0, s34
	s_nop 0
	global_load_lds_dwordx4 v[174:175], off
	v_lshl_add_u64 v[174:175], s[2:3], 0, v[128:129]
	s_add_i32 m0, s34, 0x2000
	s_nop 0
	global_load_lds_dwordx4 v[174:175], off
	v_lshl_add_u64 v[174:175], v[180:181], 0, s[76:77]
	s_mov_b32 m0, s45
	s_nop 0
	global_load_lds_dwordx4 v[174:175], off
	v_lshl_add_u64 v[174:175], v[198:199], 0, s[76:77]
	s_mov_b32 m0, s46
	s_nop 0
	global_load_lds_dwordx4 v[174:175], off
	s_waitcnt vmcnt(8)
	s_waitcnt lgkmcnt(0)
	s_barrier
	v_mfma_f32_16x16x32_bf16 v[60:63], v[146:149], v[202:205], v[60:63]
	v_mfma_f32_16x16x32_bf16 v[52:55], v[154:157], v[202:205], v[52:55]
	v_mfma_f32_16x16x32_bf16 v[44:47], v[146:149], v[210:213], v[44:47]
	v_mfma_f32_16x16x32_bf16 v[36:39], v[154:157], v[210:213], v[36:39]
	v_mfma_f32_16x16x32_bf16 v[28:31], v[146:149], v[226:229], v[28:31]
	v_mfma_f32_16x16x32_bf16 v[20:23], v[154:157], v[226:229], v[20:23]
	v_mfma_f32_16x16x32_bf16 v[12:15], v[146:149], v[234:237], v[12:15]
	v_mfma_f32_16x16x32_bf16 v[4:7], v[154:157], v[234:237], v[4:7]
	v_mfma_f32_16x16x32_bf16 v[60:63], v[150:153], v[206:209], v[60:63]
	v_mfma_f32_16x16x32_bf16 v[52:55], v[158:161], v[206:209], v[52:55]
	v_mfma_f32_16x16x32_bf16 v[44:47], v[150:153], v[214:217], v[44:47]
	v_mfma_f32_16x16x32_bf16 v[36:39], v[158:161], v[214:217], v[36:39]
	v_mfma_f32_16x16x32_bf16 v[28:31], v[150:153], v[230:233], v[28:31]
	v_mfma_f32_16x16x32_bf16 v[20:23], v[158:161], v[230:233], v[20:23]
	v_mfma_f32_16x16x32_bf16 v[12:15], v[150:153], v[238:241], v[12:15]
	v_mfma_f32_16x16x32_bf16 v[4:7], v[158:161], v[238:241], v[4:7]
	v_mfma_f32_16x16x32_bf16 v[56:59], v[162:165], v[202:205], v[56:59]
	v_mfma_f32_16x16x32_bf16 v[48:51], v[170:173], v[202:205], v[48:51]
	v_mfma_f32_16x16x32_bf16 v[40:43], v[162:165], v[210:213], v[40:43]
	v_mfma_f32_16x16x32_bf16 v[32:35], v[170:173], v[210:213], v[32:35]
	v_mfma_f32_16x16x32_bf16 v[24:27], v[162:165], v[226:229], v[24:27]
	v_mfma_f32_16x16x32_bf16 v[16:19], v[170:173], v[226:229], v[16:19]
	v_mfma_f32_16x16x32_bf16 v[8:11], v[162:165], v[234:237], v[8:11]
	v_mfma_f32_16x16x32_bf16 v[0:3], v[170:173], v[234:237], v[0:3]
	v_mfma_f32_16x16x32_bf16 v[56:59], v[166:169], v[206:209], v[56:59]
	v_mfma_f32_16x16x32_bf16 v[48:51], v[194:197], v[206:209], v[48:51]
	v_mfma_f32_16x16x32_bf16 v[40:43], v[166:169], v[214:217], v[40:43]
	v_mfma_f32_16x16x32_bf16 v[32:35], v[194:197], v[214:217], v[32:35]
	v_mfma_f32_16x16x32_bf16 v[24:27], v[166:169], v[230:233], v[24:27]
	v_mfma_f32_16x16x32_bf16 v[16:19], v[194:197], v[230:233], v[16:19]
	v_mfma_f32_16x16x32_bf16 v[8:11], v[166:169], v[238:241], v[8:11]
	v_mfma_f32_16x16x32_bf16 v[0:3], v[194:197], v[238:241], v[0:3]
	s_barrier
	s_add_i32 s55, s55, 2
	s_add_u32 s53, s53, 0x100
	s_addc_u32 s54, s54, 0
	s_mov_b64 s[2:3], s[28:29]
	.p2align 6
